# final candidate 2: PF folded normalisation (deferred staging) + zero-SrcC peeled first K iteration in PG/PH/In/Vt/GLU/S3 loops + coalesced epilogue stores
# speedup vs baseline: 1.0107x; 1.0043x over previous
; #define PG8_STAGE(bufoff, gbase, voff) do { _Pragma("unroll") for (int _i = 0; _i < 2; ++_i) \
;         __builtin_amdgcn_global_load_lds((const unsigned*)((const char*)(gbase) + (voff)[_i]), (LAS unsigned*)(lds + (bufoff) + ldsw + _i * 8192), 16, 0, 0); } while (0)
; #define PG8_LDA(dst, b, h) do { _Pragma("unroll") for (int m = 0; m < 4; ++m) _Pragma("unroll") for (int k = 0; k < 2; ++k) dst[m][k] = *(const LAS bf16x8*)(lds + PG8_SA(b, h) + aoff + m * 2048 + k * 1024); } while (0)
; #define PG8_LDB(dst, b, h) do { _Pragma("unroll") for (int n = 0; n < 2; ++n) _Pragma("unroll") for (int k = 0; k < 2; ++k) dst[n][k] = *(const LAS bf16x8*)(lds + PG8_SB(b, h) + boff + n * 2048 + k * 1024); } while (0)
; #define PG8_WAIT_V(n) asm volatile("s_waitcnt vmcnt(" #n ")" ::: "memory")
; #define PG8_WAIT_L(n) asm volatile("s_waitcnt lgkmcnt(" #n ")" ::: "memory")
; #define PG8_BAR __builtin_amdgcn_s_barrier()
; #define PG8_SCHED __builtin_amdgcn_sched_barrier(0)
; template <class Epi, class Sched, bool ALIGN_EPI>
; __device__ __forceinline__ void gemm_phase(LAS unsigned char* lds, const Gemm g, const Sched& S, const Epi& E) {
;     ...
;         const bool has_next = S.next(ui + 1, nxt);
;         const char* nA = has_next ? (const char*)g.A + (size_t)nxt.pm * tstepA : cA; const char* nB = has_next ? (const char*)g.Bt + (size_t)nxt.pn * tstepB : cB;
;         for (int t = 0; t < nt; t += 2) {
;             const bool last = (t == nt - 2);
;             const char* a1 = cA + (size_t)(t + 1) * kstep;
;             const char* a2 = last ? nA : cA + (size_t)(t + 2) * kstep; const char* b2 = last ? nB : cB + (size_t)(t + 2) * kstep;
;             const char* a3 = a2 + kstep; const char* b3 = b2 + kstep;
;             PG8_LDB(B0, 0, 0); PG8_LDB(B1, 0, 1); PG8_SCHED; PG8_LDA(At, 0, 0); PG8_STAGE(PG8_SA(1, 1), a1 + hstepA, voffA);
;             PG8_WAIT_V(8); PG8_WAIT_L(0); PG8_BAR; PG8_MMA(0, 0, At, B0); PG8_MMA(0, 1, At, B1); PG8_BAR; PG8_SCHED;
;             PG8_LDA(At, 0, 1); PG8_STAGE(PG8_SB(0, 0), b2, voffB); PG8_STAGE(PG8_SB(0, 1), b2 + hstepB, voffB); PG8_STAGE(PG8_SA(0, 0), a2, voffA);
;     ...
;         for (int a = 0; a < 2; ++a)
; #pragma unroll
;             for (int b = 0; b < 2; ++b)
; #pragma unroll
;                 for (int m = 0; m < 4; ++m)
; #pragma unroll
;                     for (int n = 0; n < 2; ++n) acc[a][b][m][n] = (f32x4){0.f, 0.f, 0.f, 0.f};
.LBB0_452:
	s_ashr_i32 s81, s80, 31
	s_lshl_b64 s[6:7], s[80:81], 19
	v_readlane_b32 s17, v255, 36
	s_add_u32 s6, s17, s6
	s_addc_u32 s7, s33, s7
	s_and_b64 s[48:49], s[42:43], exec
	s_cselect_b32 s54, s7, s47
	s_cselect_b32 s55, s6, s46
	s_ashr_i32 s17, s16, 31
	s_lshl_b64 s[48:49], s[16:17], 19
	v_readlane_b32 s17, v255, 46
	s_add_u32 s62, s17, s48
	v_readlane_b32 s17, v255, 48
	s_addc_u32 s63, s17, s49
	s_and_b64 s[48:49], s[42:43], exec
	s_cselect_b32 s17, s63, s9
	s_cselect_b32 s56, s62, s8
	s_add_u32 s46, s46, 0x40080
	s_addc_u32 s47, s47, 0
	s_add_u32 s57, s8, 0x100
	s_addc_u32 s64, s9, 0
	s_mov_b32 s65, -2
	s_add_u32 s8, s46, 0xfffc0080
	s_addc_u32 s9, s47, -1
	s_add_i32 s66, 0, 0x10000
	s_cmp_eq_u32 s65, 12
	s_cselect_b32 s49, s54, s9
	s_cselect_b32 s48, s55, s8
	s_cselect_b32 s9, s17, s64
	s_cselect_b32 s8, s56, s57
	s_add_i32 s76, 0, 0x14000
	v_add_u32_e32 v52, s66, v178
	v_add_u32_e32 v168, s76, v178
	ds_read_b128 v[40:43], v52
	ds_read_b128 v[44:47], v52 offset:1024
	ds_read_b128 v[48:51], v52 offset:2048
	ds_read_b128 v[52:55], v52 offset:3072
	ds_read_b128 v[156:159], v168
	ds_read_b128 v[160:163], v168 offset:1024
	ds_read_b128 v[164:167], v168 offset:2048
	ds_read_b128 v[168:171], v168 offset:3072
	v_lshl_add_u64 v[194:195], s[46:47], 0, v[152:153]
	s_add_i32 m0, s50, 0xc000
	ds_read_b128 v[172:175], v179
	ds_read_b128 v[180:183], v179 offset:1024
	ds_read_b128 v[184:187], v179 offset:2048
	ds_read_b128 v[188:191], v179 offset:3072
	ds_read_b128 v[212:215], v179 offset:4096
	ds_read_b128 v[216:219], v179 offset:5120
	ds_read_b128 v[220:223], v179 offset:6144
	ds_read_b128 v[224:227], v179 offset:7168
	global_load_lds_dwordx4 v[194:195], off
	v_lshl_add_u64 v[194:195], s[46:47], 0, v[154:155]
	s_add_i32 m0, s50, 0xe000
	s_nop 0
	global_load_lds_dwordx4 v[194:195], off
	s_waitcnt vmcnt(8)
	s_waitcnt lgkmcnt(0)
	s_barrier
	s_setprio 1
	s_waitcnt lgkmcnt(0)
	v_mfma_f32_16x16x32_bf16 v[140:143], v[40:43], v[172:175], 0
	v_mfma_f32_16x16x32_bf16 v[136:139], v[48:51], v[172:175], 0
	v_mfma_f32_16x16x32_bf16 v[124:127], v[40:43], v[184:187], 0
	v_mfma_f32_16x16x32_bf16 v[120:123], v[48:51], v[184:187], 0
	v_mfma_f32_16x16x32_bf16 v[108:111], v[40:43], v[212:215], 0
	v_mfma_f32_16x16x32_bf16 v[104:107], v[48:51], v[212:215], 0
	v_mfma_f32_16x16x32_bf16 v[92:95], v[40:43], v[220:223], 0
	v_mfma_f32_16x16x32_bf16 v[88:91], v[48:51], v[220:223], 0
	v_mfma_f32_16x16x32_bf16 v[140:143], v[44:47], v[180:183], v[140:143]
	v_mfma_f32_16x16x32_bf16 v[136:139], v[52:55], v[180:183], v[136:139]
	v_mfma_f32_16x16x32_bf16 v[124:127], v[44:47], v[188:191], v[124:127]
	v_mfma_f32_16x16x32_bf16 v[120:123], v[52:55], v[188:191], v[120:123]
	v_mfma_f32_16x16x32_bf16 v[108:111], v[44:47], v[216:219], v[108:111]
	v_mfma_f32_16x16x32_bf16 v[104:107], v[52:55], v[216:219], v[104:107]
	v_mfma_f32_16x16x32_bf16 v[92:95], v[44:47], v[224:227], v[92:95]
	v_mfma_f32_16x16x32_bf16 v[88:91], v[52:55], v[224:227], v[88:91]
	s_setprio 0
	s_setprio 1
	v_mfma_f32_16x16x32_bf16 v[132:135], v[156:159], v[172:175], 0
	v_mfma_f32_16x16x32_bf16 v[128:131], v[164:167], v[172:175], 0
	v_mfma_f32_16x16x32_bf16 v[116:119], v[156:159], v[184:187], 0
	v_mfma_f32_16x16x32_bf16 v[112:115], v[164:167], v[184:187], 0
	v_mfma_f32_16x16x32_bf16 v[100:103], v[156:159], v[212:215], 0
	v_mfma_f32_16x16x32_bf16 v[96:99], v[164:167], v[212:215], 0
	v_mfma_f32_16x16x32_bf16 v[84:87], v[156:159], v[220:223], 0
	v_mfma_f32_16x16x32_bf16 v[80:83], v[164:167], v[220:223], 0
	v_mfma_f32_16x16x32_bf16 v[132:135], v[160:163], v[180:183], v[132:135]
	v_mfma_f32_16x16x32_bf16 v[128:131], v[168:171], v[180:183], v[128:131]
	v_mfma_f32_16x16x32_bf16 v[116:119], v[160:163], v[188:191], v[116:119]
	v_mfma_f32_16x16x32_bf16 v[112:115], v[168:171], v[188:191], v[112:115]
	v_mfma_f32_16x16x32_bf16 v[100:103], v[160:163], v[216:219], v[100:103]
	v_mfma_f32_16x16x32_bf16 v[96:99], v[168:171], v[216:219], v[96:99]
	v_mfma_f32_16x16x32_bf16 v[84:87], v[160:163], v[224:227], v[84:87]
	v_mfma_f32_16x16x32_bf16 v[80:83], v[168:171], v[224:227], v[80:83]
	s_setprio 0
	s_barrier
	s_add_i32 s66, s66, s53
	v_lshl_add_u64 v[194:195], s[8:9], 0, v[148:149]
	s_mov_b32 m0, s66
	ds_read_b128 v[172:175], v179 offset:16384
	ds_read_b128 v[180:183], v179 offset:17408
	ds_read_b128 v[184:187], v179 offset:18432
	ds_read_b128 v[188:191], v179 offset:19456
	ds_read_b128 v[212:215], v179 offset:20480
	ds_read_b128 v[216:219], v179 offset:21504
	ds_read_b128 v[220:223], v179 offset:22528
	ds_read_b128 v[224:227], v179 offset:23552
	global_load_lds_dwordx4 v[194:195], off
	s_add_i32 m0, s66, 0x2000
	s_add_u32 s66, s8, 0x40000
	v_lshl_add_u64 v[196:197], s[8:9], 0, v[144:145]
	s_addc_u32 s67, s9, 0
	s_add_i32 s76, s76, s53
	global_load_lds_dwordx4 v[196:197], off
	v_lshl_add_u64 v[198:199], s[66:67], 0, v[148:149]
	s_mov_b32 m0, s76
	v_lshl_add_u64 v[200:201], s[48:49], 0, v[146:147]
	global_load_lds_dwordx4 v[198:199], off
	v_lshl_add_u64 v[198:199], s[66:67], 0, v[144:145]
	s_add_i32 m0, s76, 0x2000
	s_nop 0
	global_load_lds_dwordx4 v[198:199], off
	v_lshl_add_u64 v[198:199], s[48:49], 0, v[150:151]
	s_mov_b32 m0, s50
	s_nop 0
	global_load_lds_dwordx4 v[198:199], off
	s_mov_b32 m0, s51
	s_nop 0
	global_load_lds_dwordx4 v[200:201], off
	s_waitcnt vmcnt(8)
	s_waitcnt lgkmcnt(0)
	s_barrier
; #define PG8_STAGE(bufoff, gbase, voff) do { _Pragma("unroll") for (int _i = 0; _i < 2; ++_i) \
;         __builtin_amdgcn_global_load_lds((const unsigned*)((const char*)(gbase) + (voff)[_i]), (LAS unsigned*)(lds + (bufoff) + ldsw + _i * 8192), 16, 0, 0); } while (0)
; #define PG8_LDA(dst, b, h) do { _Pragma("unroll") for (int m = 0; m < 4; ++m) _Pragma("unroll") for (int k = 0; k < 2; ++k) dst[m][k] = *(const LAS bf16x8*)(lds + PG8_SA(b, h) + aoff + m * 2048 + k * 1024); } while (0)
; #define PG8_LDB(dst, b, h) do { _Pragma("unroll") for (int n = 0; n < 2; ++n) _Pragma("unroll") for (int k = 0; k < 2; ++k) dst[n][k] = *(const LAS bf16x8*)(lds + PG8_SB(b, h) + boff + n * 2048 + k * 1024); } while (0)
; #define PG8_MMA(ai, bj, At, Bt) do { __builtin_amdgcn_s_setprio(1); _Pragma("unroll") for (int m = 0; m < 4; ++m) _Pragma("unroll") for (int n = 0; n < 2; ++n) _Pragma("unroll") for (int k = 0; k < 2; ++k) \
;         acc[ai][bj][m][n] = __builtin_amdgcn_mfma_f32_16x16x32_bf16(Bt[n][k], At[m][k], acc[ai][bj][m][n], 0, 0, 0); __builtin_amdgcn_s_setprio(0); } while (0)
; #define PG8_WAIT_V(n) asm volatile("s_waitcnt vmcnt(" #n ")" ::: "memory")
; #define PG8_WAIT_L(n) asm volatile("s_waitcnt lgkmcnt(" #n ")" ::: "memory")
; #define PG8_BAR __builtin_amdgcn_s_barrier()
; #define PG8_SCHED __builtin_amdgcn_sched_barrier(0)
; template <class Epi, class Sched, bool ALIGN_EPI>
; __device__ __forceinline__ void gemm_phase(LAS unsigned char* lds, const Gemm g, const Sched& S, const Epi& E) {
;     ...
;             PG8_LDA(At, 0, 1); PG8_STAGE(PG8_SB(0, 0), b2, voffB); PG8_STAGE(PG8_SB(0, 1), b2 + hstepB, voffB); PG8_STAGE(PG8_SA(0, 0), a2, voffA);
;             PG8_WAIT_V(8); PG8_WAIT_L(0); PG8_BAR; PG8_MMA(1, 0, At, B0); PG8_MMA(1, 1, At, B1); PG8_BAR; PG8_SCHED;
;             PG8_LDB(B0, 1, 0); PG8_LDB(B1, 1, 1); PG8_SCHED; PG8_LDA(At, 1, 0); PG8_STAGE(PG8_SA(0, 1), a2 + hstepA, voffA);
;             PG8_WAIT_V(8); PG8_WAIT_L(0); PG8_BAR; PG8_MMA(0, 0, At, B0); PG8_MMA(0, 1, At, B1); PG8_BAR; PG8_SCHED;
	s_setprio 1
	s_waitcnt lgkmcnt(0)
	v_mfma_f32_16x16x32_bf16 v[76:79], v[40:43], v[172:175], 0
	v_mfma_f32_16x16x32_bf16 v[72:75], v[48:51], v[172:175], 0
	v_mfma_f32_16x16x32_bf16 v[60:63], v[40:43], v[184:187], 0
	v_mfma_f32_16x16x32_bf16 v[56:59], v[48:51], v[184:187], 0
	v_mfma_f32_16x16x32_bf16 v[28:31], v[40:43], v[212:215], 0
	v_mfma_f32_16x16x32_bf16 v[24:27], v[48:51], v[212:215], 0
	v_mfma_f32_16x16x32_bf16 v[12:15], v[40:43], v[220:223], 0
	v_mfma_f32_16x16x32_bf16 v[8:11], v[48:51], v[220:223], 0
	v_mfma_f32_16x16x32_bf16 v[76:79], v[44:47], v[180:183], v[76:79]
	v_mfma_f32_16x16x32_bf16 v[72:75], v[52:55], v[180:183], v[72:75]
	v_mfma_f32_16x16x32_bf16 v[60:63], v[44:47], v[188:191], v[60:63]
	v_mfma_f32_16x16x32_bf16 v[56:59], v[52:55], v[188:191], v[56:59]
	v_mfma_f32_16x16x32_bf16 v[28:31], v[44:47], v[216:219], v[28:31]
	v_mfma_f32_16x16x32_bf16 v[24:27], v[52:55], v[216:219], v[24:27]
	v_mfma_f32_16x16x32_bf16 v[12:15], v[44:47], v[224:227], v[12:15]
	v_mfma_f32_16x16x32_bf16 v[8:11], v[52:55], v[224:227], v[8:11]
	s_setprio 0
	s_setprio 1
	v_mfma_f32_16x16x32_bf16 v[36:39], v[156:159], v[184:187], 0
	v_mfma_f32_16x16x32_bf16 v[32:35], v[164:167], v[184:187], 0
	v_mfma_f32_16x16x32_bf16 v[20:23], v[156:159], v[212:215], 0
	v_mfma_f32_16x16x32_bf16 v[16:19], v[164:167], v[212:215], 0
	v_mfma_f32_16x16x32_bf16 v[4:7], v[156:159], v[220:223], 0
	v_mfma_f32_16x16x32_bf16 v[0:3], v[164:167], v[220:223], 0
	v_mfma_f32_16x16x32_bf16 v[40:43], v[156:159], v[172:175], 0
	v_mfma_f32_16x16x32_bf16 v[44:47], v[164:167], v[172:175], 0
	v_mfma_f32_16x16x32_bf16 v[36:39], v[160:163], v[188:191], v[36:39]
	v_mfma_f32_16x16x32_bf16 v[32:35], v[168:171], v[188:191], v[32:35]
	v_mfma_f32_16x16x32_bf16 v[20:23], v[160:163], v[216:219], v[20:23]
	v_mfma_f32_16x16x32_bf16 v[16:19], v[168:171], v[216:219], v[16:19]
	v_mfma_f32_16x16x32_bf16 v[4:7], v[160:163], v[224:227], v[4:7]
	v_mfma_f32_16x16x32_bf16 v[0:3], v[168:171], v[224:227], v[0:3]
	v_mfma_f32_16x16x32_bf16 v[40:43], v[160:163], v[180:183], v[40:43]
	v_mfma_f32_16x16x32_bf16 v[44:47], v[168:171], v[180:183], v[44:47]
	s_setprio 0
	s_barrier
	s_add_i32 s66, 0, 0x18000
	s_add_i32 s67, 0, 0x1c000
	v_add_u32_e32 v68, s66, v178
	v_add_u32_e32 v168, s67, v178
	ds_read_b128 v[48:51], v68
	ds_read_b128 v[52:55], v68 offset:1024
	ds_read_b128 v[64:67], v68 offset:2048
	ds_read_b128 v[68:71], v68 offset:3072
	ds_read_b128 v[156:159], v168
	ds_read_b128 v[160:163], v168 offset:1024
	ds_read_b128 v[164:167], v168 offset:2048
	ds_read_b128 v[168:171], v168 offset:3072
	s_add_u32 s48, s48, 0x40000
	s_addc_u32 s49, s49, 0
	s_mov_b32 m0, s22
	v_lshl_add_u64 v[202:203], s[48:49], 0, v[150:151]
	ds_read_b128 v[172:175], v179 offset:32768
	ds_read_b128 v[180:183], v179 offset:33792
	ds_read_b128 v[184:187], v179 offset:34816
	ds_read_b128 v[188:191], v179 offset:35840
	ds_read_b128 v[212:215], v179 offset:36864
	ds_read_b128 v[216:219], v179 offset:37888
	ds_read_b128 v[220:223], v179 offset:38912
	ds_read_b128 v[224:227], v179 offset:39936
	global_load_lds_dwordx4 v[202:203], off
	v_lshl_add_u64 v[202:203], s[48:49], 0, v[146:147]
	s_mov_b32 m0, s23
	s_nop 0
	global_load_lds_dwordx4 v[202:203], off
	s_waitcnt vmcnt(8)
	s_waitcnt lgkmcnt(0)
	s_barrier
	s_setprio 1
	s_waitcnt lgkmcnt(0)
	v_mfma_f32_16x16x32_bf16 v[140:143], v[48:51], v[172:175], v[140:143]
	v_mfma_f32_16x16x32_bf16 v[136:139], v[64:67], v[172:175], v[136:139]
	v_mfma_f32_16x16x32_bf16 v[124:127], v[48:51], v[184:187], v[124:127]
	v_mfma_f32_16x16x32_bf16 v[120:123], v[64:67], v[184:187], v[120:123]
	v_mfma_f32_16x16x32_bf16 v[108:111], v[48:51], v[212:215], v[108:111]
	v_mfma_f32_16x16x32_bf16 v[104:107], v[64:67], v[212:215], v[104:107]
	v_mfma_f32_16x16x32_bf16 v[92:95], v[48:51], v[220:223], v[92:95]
	v_mfma_f32_16x16x32_bf16 v[88:91], v[64:67], v[220:223], v[88:91]
	v_mfma_f32_16x16x32_bf16 v[140:143], v[52:55], v[180:183], v[140:143]
	v_mfma_f32_16x16x32_bf16 v[136:139], v[68:71], v[180:183], v[136:139]
	v_mfma_f32_16x16x32_bf16 v[124:127], v[52:55], v[188:191], v[124:127]
	v_mfma_f32_16x16x32_bf16 v[120:123], v[68:71], v[188:191], v[120:123]
	v_mfma_f32_16x16x32_bf16 v[108:111], v[52:55], v[216:219], v[108:111]
	v_mfma_f32_16x16x32_bf16 v[104:107], v[68:71], v[216:219], v[104:107]
	v_mfma_f32_16x16x32_bf16 v[92:95], v[52:55], v[224:227], v[92:95]
	v_mfma_f32_16x16x32_bf16 v[88:91], v[68:71], v[224:227], v[88:91]
	s_setprio 0
	s_setprio 1
	v_mfma_f32_16x16x32_bf16 v[132:135], v[156:159], v[172:175], v[132:135]
	v_mfma_f32_16x16x32_bf16 v[128:131], v[164:167], v[172:175], v[128:131]
	v_mfma_f32_16x16x32_bf16 v[116:119], v[156:159], v[184:187], v[116:119]
	v_mfma_f32_16x16x32_bf16 v[112:115], v[164:167], v[184:187], v[112:115]
	v_mfma_f32_16x16x32_bf16 v[100:103], v[156:159], v[212:215], v[100:103]
	v_mfma_f32_16x16x32_bf16 v[96:99], v[164:167], v[212:215], v[96:99]
	v_mfma_f32_16x16x32_bf16 v[84:87], v[156:159], v[220:223], v[84:87]
	v_mfma_f32_16x16x32_bf16 v[80:83], v[164:167], v[220:223], v[80:83]
	v_mfma_f32_16x16x32_bf16 v[132:135], v[160:163], v[180:183], v[132:135]
	v_mfma_f32_16x16x32_bf16 v[128:131], v[168:171], v[180:183], v[128:131]
	v_mfma_f32_16x16x32_bf16 v[116:119], v[160:163], v[188:191], v[116:119]
	v_mfma_f32_16x16x32_bf16 v[112:115], v[168:171], v[188:191], v[112:115]
	v_mfma_f32_16x16x32_bf16 v[100:103], v[160:163], v[216:219], v[100:103]
	v_mfma_f32_16x16x32_bf16 v[96:99], v[168:171], v[216:219], v[96:99]
	v_mfma_f32_16x16x32_bf16 v[84:87], v[160:163], v[224:227], v[84:87]
	v_mfma_f32_16x16x32_bf16 v[80:83], v[168:171], v[224:227], v[80:83]
	s_setprio 0
	s_barrier
; #define PG8_STAGE(bufoff, gbase, voff) do { _Pragma("unroll") for (int _i = 0; _i < 2; ++_i) \
;         __builtin_amdgcn_global_load_lds((const unsigned*)((const char*)(gbase) + (voff)[_i]), (LAS unsigned*)(lds + (bufoff) + ldsw + _i * 8192), 16, 0, 0); } while (0)
; #define PG8_LDA(dst, b, h) do { _Pragma("unroll") for (int m = 0; m < 4; ++m) _Pragma("unroll") for (int k = 0; k < 2; ++k) dst[m][k] = *(const LAS bf16x8*)(lds + PG8_SA(b, h) + aoff + m * 2048 + k * 1024); } while (0)
; #define PG8_MMA(ai, bj, At, Bt) do { __builtin_amdgcn_s_setprio(1); _Pragma("unroll") for (int m = 0; m < 4; ++m) _Pragma("unroll") for (int n = 0; n < 2; ++n) _Pragma("unroll") for (int k = 0; k < 2; ++k) \
;         acc[ai][bj][m][n] = __builtin_amdgcn_mfma_f32_16x16x32_bf16(Bt[n][k], At[m][k], acc[ai][bj][m][n], 0, 0, 0); __builtin_amdgcn_s_setprio(0); } while (0)
; #define PG8_WAIT_V(n) asm volatile("s_waitcnt vmcnt(" #n ")" ::: "memory")
; #define PG8_WAIT_L(n) asm volatile("s_waitcnt lgkmcnt(" #n ")" ::: "memory")
; #define PG8_BAR __builtin_amdgcn_s_barrier()
; #define PG8_SCHED __builtin_amdgcn_sched_barrier(0)
; template <class Epi, class Sched, bool ALIGN_EPI>
; __device__ __forceinline__ void gemm_phase(LAS unsigned char* lds, const Gemm g, const Sched& S, const Epi& E) {
;     ...
;         for (int t = 0; t < nt; t += 2) {
;             const bool last = (t == nt - 2);
;             const char* a1 = cA + (size_t)(t + 1) * kstep;
;     ...
;             PG8_LDA(At, 1, 1); PG8_STAGE(PG8_SB(1, 0), b3, voffB); PG8_STAGE(PG8_SB(1, 1), b3 + hstepB, voffB); PG8_STAGE(PG8_SA(1, 0), a3, voffA);
;             PG8_WAIT_V(8); PG8_WAIT_L(0); PG8_BAR; PG8_MMA(1, 0, At, B0); PG8_MMA(1, 1, At, B1); PG8_BAR; PG8_SCHED;
	s_add_i32 s48, s66, s53
	v_lshl_add_u64 v[194:195], v[194:195], 0, s[12:13]
	s_mov_b32 m0, s48
	ds_read_b128 v[172:175], v179 offset:49152
	ds_read_b128 v[180:183], v179 offset:50176
	ds_read_b128 v[184:187], v179 offset:51200
	ds_read_b128 v[188:191], v179 offset:52224
	ds_read_b128 v[212:215], v179 offset:53248
	ds_read_b128 v[216:219], v179 offset:54272
	ds_read_b128 v[220:223], v179 offset:55296
	ds_read_b128 v[224:227], v179 offset:56320
	global_load_lds_dwordx4 v[194:195], off
	s_add_i32 m0, s48, 0x2000
	s_add_u32 s8, s8, 0x40080
	v_lshl_add_u64 v[194:195], v[196:197], 0, s[12:13]
	s_addc_u32 s9, s9, 0
	s_add_i32 s48, s67, s53
	global_load_lds_dwordx4 v[194:195], off
	v_lshl_add_u64 v[194:195], s[8:9], 0, v[148:149]
	s_mov_b32 m0, s48
	s_nop 0
	global_load_lds_dwordx4 v[194:195], off
	v_lshl_add_u64 v[194:195], s[8:9], 0, v[144:145]
	s_add_i32 m0, s48, 0x2000
	s_nop 0
	global_load_lds_dwordx4 v[194:195], off
	v_lshl_add_u64 v[194:195], v[198:199], 0, s[12:13]
	s_mov_b32 m0, s20
	s_nop 0
	global_load_lds_dwordx4 v[194:195], off
	v_lshl_add_u64 v[194:195], v[200:201], 0, s[12:13]
	s_mov_b32 m0, s21
	s_nop 0
	global_load_lds_dwordx4 v[194:195], off
	s_waitcnt vmcnt(8)
	s_waitcnt lgkmcnt(0)
	s_barrier
	s_setprio 1
	s_waitcnt lgkmcnt(0)
	v_mfma_f32_16x16x32_bf16 v[76:79], v[48:51], v[172:175], v[76:79]
	v_mfma_f32_16x16x32_bf16 v[72:75], v[64:67], v[172:175], v[72:75]
	v_mfma_f32_16x16x32_bf16 v[60:63], v[48:51], v[184:187], v[60:63]
	v_mfma_f32_16x16x32_bf16 v[56:59], v[64:67], v[184:187], v[56:59]
	v_mfma_f32_16x16x32_bf16 v[28:31], v[48:51], v[212:215], v[28:31]
	v_mfma_f32_16x16x32_bf16 v[24:27], v[64:67], v[212:215], v[24:27]
	v_mfma_f32_16x16x32_bf16 v[12:15], v[48:51], v[220:223], v[12:15]
	v_mfma_f32_16x16x32_bf16 v[8:11], v[64:67], v[220:223], v[8:11]
	v_mfma_f32_16x16x32_bf16 v[76:79], v[52:55], v[180:183], v[76:79]
	v_mfma_f32_16x16x32_bf16 v[72:75], v[68:71], v[180:183], v[72:75]
	v_mfma_f32_16x16x32_bf16 v[60:63], v[52:55], v[188:191], v[60:63]
	v_mfma_f32_16x16x32_bf16 v[56:59], v[68:71], v[188:191], v[56:59]
	v_mfma_f32_16x16x32_bf16 v[28:31], v[52:55], v[216:219], v[28:31]
	v_mfma_f32_16x16x32_bf16 v[24:27], v[68:71], v[216:219], v[24:27]
	v_mfma_f32_16x16x32_bf16 v[12:15], v[52:55], v[224:227], v[12:15]
	v_mfma_f32_16x16x32_bf16 v[8:11], v[68:71], v[224:227], v[8:11]
	s_setprio 0
	s_setprio 1
	v_mfma_f32_16x16x32_bf16 v[40:43], v[156:159], v[172:175], v[40:43]
	v_mfma_f32_16x16x32_bf16 v[68:71], v[160:163], v[180:183], v[40:43]
	v_mfma_f32_16x16x32_bf16 v[40:43], v[164:167], v[172:175], v[44:47]
	v_mfma_f32_16x16x32_bf16 v[36:39], v[156:159], v[184:187], v[36:39]
	v_mfma_f32_16x16x32_bf16 v[32:35], v[164:167], v[184:187], v[32:35]
	v_mfma_f32_16x16x32_bf16 v[20:23], v[156:159], v[212:215], v[20:23]
	v_mfma_f32_16x16x32_bf16 v[16:19], v[164:167], v[212:215], v[16:19]
	v_mfma_f32_16x16x32_bf16 v[4:7], v[156:159], v[220:223], v[4:7]
	v_mfma_f32_16x16x32_bf16 v[0:3], v[164:167], v[220:223], v[0:3]
	v_mfma_f32_16x16x32_bf16 v[64:67], v[168:171], v[180:183], v[40:43]
	v_mfma_f32_16x16x32_bf16 v[36:39], v[160:163], v[188:191], v[36:39]
	v_mfma_f32_16x16x32_bf16 v[32:35], v[168:171], v[188:191], v[32:35]
	v_mfma_f32_16x16x32_bf16 v[20:23], v[160:163], v[216:219], v[20:23]
	v_mfma_f32_16x16x32_bf16 v[16:19], v[168:171], v[216:219], v[16:19]
	v_mfma_f32_16x16x32_bf16 v[4:7], v[160:163], v[224:227], v[4:7]
	v_mfma_f32_16x16x32_bf16 v[0:3], v[168:171], v[224:227], v[0:3]
	s_setprio 0
	s_barrier
	s_add_i32 s65, s65, 2
	s_add_u32 s46, s46, 0x100
	s_addc_u32 s47, s47, 0
	s_add_u32 s57, s57, 0x100
	s_addc_u32 s64, s64, 0
	s_cmp_gt_u32 s65, 13
